# ATTN ping-pong: nop-free COMPUTE + the next iteration's pre-barrier work (scalars, vmcnt wait, mask conversion, DMA addresses) inside the last MFMA gaps
# speedup vs baseline: 1.0131x; 1.0131x over previous
.Lpp_hb:
	s_waitcnt lgkmcnt(0)
	s_barrier
	s_add_i32 s7, s6, 0x6000
	s_mov_b32 m0, s6
	global_load_lds_dwordx4 v[6:7], off
	s_mov_b32 m0, s7
	global_load_lds_dwordx4 v[8:9], off
	s_add_i32 s6, s15, -1
	s_cmp_lt_u32 s35, 63
	s_cselect_b32 s10, s6, 63
	s_lshl_b64 s[6:7], s[10:11], 15
	v_lshl_add_u64 v[6:7], v[136:137], 0, s[6:7]
	global_load_dwordx2 v[138:139], v[6:7], off
	s_cmp_gt_u32 s35, s28
	s_cbranch_scc1 .Lpp_skip
	v_add_u32_e32 v149, s5, v140
	v_add_u32_e32 v150, s5, v141
	v_add_u32_sdwa v230, v4, s25 dst_sel:DWORD dst_unused:UNUSED_PAD src0_sel:BYTE_0 src1_sel:DWORD
	v_add_u32_sdwa v231, v4, s25 dst_sel:DWORD dst_unused:UNUSED_PAD src0_sel:BYTE_1 src1_sel:DWORD
	v_add_u32_sdwa v232, v4, s25 dst_sel:DWORD dst_unused:UNUSED_PAD src0_sel:BYTE_2 src1_sel:DWORD
	v_add_u32_sdwa v233, v4, s25 dst_sel:DWORD dst_unused:UNUSED_PAD src0_sel:BYTE_3 src1_sel:DWORD
	v_add_u32_sdwa v234, v3, s25 dst_sel:DWORD dst_unused:UNUSED_PAD src0_sel:BYTE_0 src1_sel:DWORD
	v_add_u32_sdwa v235, v3, s25 dst_sel:DWORD dst_unused:UNUSED_PAD src0_sel:BYTE_1 src1_sel:DWORD
	v_add_u32_sdwa v236, v3, s25 dst_sel:DWORD dst_unused:UNUSED_PAD src0_sel:BYTE_2 src1_sel:DWORD
	v_add_u32_sdwa v237, v3, s25 dst_sel:DWORD dst_unused:UNUSED_PAD src0_sel:BYTE_3 src1_sel:DWORD
	ds_read_b128 v[66:69], v230
	ds_read_b128 v[70:73], v231
	ds_read_b128 v[74:77], v232
	ds_read_b128 v[78:81], v233
	ds_read_b128 v[182:185], v149
	ds_read_b128 v[186:189], v149 offset:2048
	ds_read_b128 v[190:193], v149 offset:4096
	ds_read_b128 v[194:197], v149 offset:6144
	ds_read_b128 v[82:85], v234
	ds_read_b128 v[86:89], v235
	ds_read_b128 v[90:93], v236
	ds_read_b128 v[94:97], v237
	s_waitcnt lgkmcnt(8)
	ds_read_b128 v[198:201], v149 offset:512
	ds_read_b128 v[202:205], v149 offset:2560
	ds_read_b128 v[206:209], v149 offset:4608
	ds_read_b128 v[210:213], v149 offset:6656
	s_waitcnt lgkmcnt(8)
	ds_read_b64_tr_b16 v[152:153], v150
	ds_read_b64_tr_b16 v[154:155], v150 offset:512
	ds_read_b64_tr_b16 v[156:157], v150 offset:1024
	ds_read_b64_tr_b16 v[158:159], v150 offset:1536
	s_waitcnt lgkmcnt(8)
	ds_read_b64_tr_b16 v[160:161], v150 offset:2048
	ds_read_b64_tr_b16 v[162:163], v150 offset:2560
	ds_read_b64_tr_b16 v[164:165], v150 offset:3072
	ds_read_b64_tr_b16 v[166:167], v150 offset:3584
	s_waitcnt lgkmcnt(8)
	ds_read_b64_tr_b16 v[168:169], v150 offset:4096
	ds_read_b64_tr_b16 v[170:171], v150 offset:4608
	ds_read_b64_tr_b16 v[172:173], v150 offset:5120
	ds_read_b64_tr_b16 v[174:175], v150 offset:5632
	s_waitcnt lgkmcnt(8)
	ds_read_b64_tr_b16 v[214:215], v150 offset:6144
	ds_read_b64_tr_b16 v[216:217], v150 offset:6656
	ds_read_b64_tr_b16 v[218:219], v150 offset:7168
	ds_read_b64_tr_b16 v[220:221], v150 offset:7680
	s_waitcnt lgkmcnt(0)
	s_barrier
	v_mfma_f32_32x32x16_bf16 v[66:81], v[182:185], v[110:113], v[66:81]
	v_mfma_f32_32x32x16_bf16 v[66:81], v[186:189], v[98:101], v[66:81]
	v_mfma_f32_32x32x16_bf16 v[66:81], v[190:193], v[102:105], v[66:81]
	v_mfma_f32_32x32x16_bf16 v[66:81], v[194:197], v[106:109], v[66:81]
	s_cmp_lt_u32 s33, s14
	s_cbranch_scc0 .Lpp_bias
	v_mfma_f32_32x32x16_bf16 v[82:97], v[198:201], v[110:113], v[82:97]
	s_add_i32 s5, s34, 1
	s_cmp_lg_u32 s34, 2
	s_cselect_b32 s34, s5, 0
	v_mfma_f32_32x32x16_bf16 v[82:97], v[202:205], v[98:101], v[82:97]
	s_addk_i32 s31, 0xff00
	s_add_i32 s15, s15, 1
	s_add_i32 s5, s30, s31
	v_mfma_f32_32x32x16_bf16 v[82:97], v[206:209], v[102:105], v[82:97]
	s_add_i32 s33, s33, 64
	s_cmp_eq_u32 s5, 0
	s_cselect_b32 s37, 1, 0
	v_exp_f32_e32 v66, v66
	v_exp_f32_e32 v67, v67
	v_exp_f32_e32 v68, v68
	v_mfma_f32_32x32x16_bf16 v[82:97], v[210:213], v[106:109], v[82:97]
	v_exp_f32_e32 v69, v69
	v_exp_f32_e32 v70, v70
	v_exp_f32_e32 v71, v71
	v_exp_f32_e32 v72, v72
	v_exp_f32_e32 v73, v73
	v_cvt_pk_bf16_f32 v4, v66, v67
	v_cvt_pk_bf16_f32 v5, v68, v69
	v_cvt_pk_bf16_f32 v6, v70, v71
	v_cvt_pk_bf16_f32 v7, v72, v73
	v_exp_f32_e32 v74, v74
	v_exp_f32_e32 v75, v75
	v_mfma_f32_32x32x16_bf16 v[34:49], v[4:7], v[152:155], v[34:49]
	v_exp_f32_e32 v76, v76
	v_exp_f32_e32 v77, v77
	v_exp_f32_e32 v78, v78
	v_mfma_f32_32x32x16_bf16 v[18:33], v[4:7], v[168:171], v[18:33]
	v_exp_f32_e32 v79, v79
	v_exp_f32_e32 v80, v80
	v_exp_f32_e32 v81, v81
	v_mfma_f32_32x32x16_bf16 v[50:65], v[4:7], v[226:229], v[50:65]
	v_cvt_pk_bf16_f32 v8, v74, v75
	v_cvt_pk_bf16_f32 v9, v76, v77
	v_cvt_pk_bf16_f32 v10, v78, v79
	v_cvt_pk_bf16_f32 v11, v80, v81
	v_exp_f32_e32 v82, v82
	v_exp_f32_e32 v83, v83
	v_mfma_f32_32x32x16_bf16 v[34:49], v[8:11], v[156:159], v[34:49]
	v_exp_f32_e32 v84, v84
	v_exp_f32_e32 v85, v85
	v_exp_f32_e32 v86, v86
	v_mfma_f32_32x32x16_bf16 v[18:33], v[8:11], v[172:175], v[18:33]
	v_exp_f32_e32 v87, v87
	v_exp_f32_e32 v88, v88
	v_exp_f32_e32 v89, v89
	v_mfma_f32_32x32x16_bf16 v[50:65], v[8:11], v[226:229], v[50:65]
	v_cvt_pk_bf16_f32 v12, v82, v83
	v_cvt_pk_bf16_f32 v13, v84, v85
	v_cvt_pk_bf16_f32 v14, v86, v87
	v_cvt_pk_bf16_f32 v15, v88, v89
	v_exp_f32_e32 v90, v90
	v_exp_f32_e32 v91, v91
	v_mfma_f32_32x32x16_bf16 v[34:49], v[12:15], v[160:163], v[34:49]
	v_exp_f32_e32 v92, v92
	v_exp_f32_e32 v93, v93
	v_exp_f32_e32 v94, v94
	s_add_i32 s35, s15, -2
	s_lshl_b32 s5, s34, 13
	s_cmp_lt_u32 s15, s27
	s_cselect_b32 s10, s15, s29
	v_mfma_f32_32x32x16_bf16 v[18:33], v[12:15], v[214:217], v[18:33]
	v_exp_f32_e32 v95, v95
	v_exp_f32_e32 v96, v96
	v_exp_f32_e32 v97, v97
	s_lshl_b64 s[6:7], s[10:11], 16
	s_waitcnt vmcnt(0)
	v_mfma_f32_32x32x16_bf16 v[50:65], v[12:15], v[226:229], v[50:65]
	v_cvt_pk_bf16_f32 v222, v90, v91
	v_cvt_pk_bf16_f32 v223, v92, v93
	v_cvt_pk_bf16_f32 v224, v94, v95
	v_cvt_pk_bf16_f32 v225, v96, v97
	v_lshl_add_u64 v[6:7], v[116:117], 0, s[6:7]
	v_lshl_add_u64 v[8:9], v[118:119], 0, s[6:7]
	v_mfma_f32_32x32x16_bf16 v[34:49], v[222:225], v[164:167], v[34:49]
	v_lshrrev_b32_e32 v3, v1, v138
	s_add_i32 s6, s5, 0xffffe000
	v_lshlrev_b32_e32 v3, 4, v3
	s_cmp_lg_u32 s34, 0
	v_and_b32_e32 v4, 0xf0f0f0f0, v3
	v_mfma_f32_32x32x16_bf16 v[18:33], v[222:225], v[218:221], v[18:33]
	v_lshrrev_b32_e32 v3, v1, v139
	s_cselect_b32 s6, s6, 0x4000
	v_lshlrev_b32_e32 v3, 4, v3
	s_add_i32 s6, s20, s6
	v_and_b32_e32 v3, 0xf0f0f0f0, v3
	v_mfma_f32_32x32x16_bf16 v[50:65], v[222:225], v[226:229], v[50:65]
	s_cmp_lg_u32 s37, 0
	s_cbranch_scc1 .LBB0_946
	s_branch .Lpp_hb
